# up-GEMM main loop: LDS-DMA loads use SGPR base + 32-bit VGPR offset, no VALU 64-bit address adds
# speedup vs baseline: 1.0078x; 1.0053x over previous
.LBB0_1151:
	s_add_u32 s20, s18, 0xfff80080
	s_addc_u32 s21, s19, -1
	s_cmp_eq_u32 s51, 28
	s_cselect_b32 s23, s15, s21
	s_cselect_b32 s22, s14, s20
	v_add_u32_e32 v0, s28, v144
	s_cselect_b32 s21, s17, s50
	s_cselect_b32 s20, s16, s13
	s_add_i32 s34, 0, 0x14000
	ds_read_b128 v[146:149], v0
	ds_read_b128 v[150:153], v0 offset:1024
	ds_read_b128 v[154:157], v0 offset:2048
	ds_read_b128 v[158:161], v0 offset:3072
	v_add_u32_e32 v0, s34, v144
	ds_read_b128 v[168:171], v0
	ds_read_b128 v[172:175], v0 offset:1024
	ds_read_b128 v[176:179], v0 offset:2048
	ds_read_b128 v[182:185], v0 offset:3072
	s_add_i32 m0, s26, 0xc000
	ds_read_b128 v[186:189], v145
	ds_read_b128 v[190:193], v145 offset:1024
	ds_read_b128 v[194:197], v145 offset:2048
	ds_read_b128 v[204:207], v145 offset:3072
	ds_read_b128 v[208:211], v145 offset:4096
	ds_read_b128 v[216:219], v145 offset:5120
	ds_read_b128 v[220:223], v145 offset:6144
	ds_read_b128 v[224:227], v145 offset:7168
	global_load_lds_dwordx4 v138, s[18:19]
	s_add_i32 m0, s26, 0xe000
	s_nop 0
	global_load_lds_dwordx4 v140, s[18:19]
	s_waitcnt vmcnt(8)
	s_waitcnt lgkmcnt(0)
	s_barrier
	s_setprio 1
	s_waitcnt lgkmcnt(0)
	v_mfma_f32_16x16x32_bf16 v[126:129], v[146:149], v[186:189], v[126:129]
	v_mfma_f32_16x16x32_bf16 v[122:125], v[154:157], v[186:189], v[122:125]
	v_mfma_f32_16x16x32_bf16 v[110:113], v[146:149], v[194:197], v[110:113]
	v_mfma_f32_16x16x32_bf16 v[106:109], v[154:157], v[194:197], v[106:109]
	v_mfma_f32_16x16x32_bf16 v[94:97], v[146:149], v[208:211], v[94:97]
	v_mfma_f32_16x16x32_bf16 v[90:93], v[154:157], v[208:211], v[90:93]
	v_mfma_f32_16x16x32_bf16 v[78:81], v[146:149], v[220:223], v[78:81]
	v_mfma_f32_16x16x32_bf16 v[74:77], v[154:157], v[220:223], v[74:77]
	v_mfma_f32_16x16x32_bf16 v[126:129], v[150:153], v[190:193], v[126:129]
	v_mfma_f32_16x16x32_bf16 v[122:125], v[158:161], v[190:193], v[122:125]
	v_mfma_f32_16x16x32_bf16 v[110:113], v[150:153], v[204:207], v[110:113]
	v_mfma_f32_16x16x32_bf16 v[106:109], v[158:161], v[204:207], v[106:109]
	v_mfma_f32_16x16x32_bf16 v[94:97], v[150:153], v[216:219], v[94:97]
	v_mfma_f32_16x16x32_bf16 v[90:93], v[158:161], v[216:219], v[90:93]
	v_mfma_f32_16x16x32_bf16 v[78:81], v[150:153], v[224:227], v[78:81]
	v_mfma_f32_16x16x32_bf16 v[74:77], v[158:161], v[224:227], v[74:77]
	s_setprio 0
	s_setprio 1
	v_mfma_f32_16x16x32_bf16 v[118:121], v[168:171], v[186:189], v[118:121]
	v_mfma_f32_16x16x32_bf16 v[114:117], v[176:179], v[186:189], v[114:117]
	v_mfma_f32_16x16x32_bf16 v[102:105], v[168:171], v[194:197], v[102:105]
	v_mfma_f32_16x16x32_bf16 v[98:101], v[176:179], v[194:197], v[98:101]
	v_mfma_f32_16x16x32_bf16 v[86:89], v[168:171], v[208:211], v[86:89]
	v_mfma_f32_16x16x32_bf16 v[82:85], v[176:179], v[208:211], v[82:85]
	v_mfma_f32_16x16x32_bf16 v[70:73], v[168:171], v[220:223], v[70:73]
	v_mfma_f32_16x16x32_bf16 v[66:69], v[176:179], v[220:223], v[66:69]
	v_mfma_f32_16x16x32_bf16 v[118:121], v[172:175], v[190:193], v[118:121]
	v_mfma_f32_16x16x32_bf16 v[114:117], v[182:185], v[190:193], v[114:117]
	v_mfma_f32_16x16x32_bf16 v[102:105], v[172:175], v[204:207], v[102:105]
	v_mfma_f32_16x16x32_bf16 v[98:101], v[182:185], v[204:207], v[98:101]
	v_mfma_f32_16x16x32_bf16 v[86:89], v[172:175], v[216:219], v[86:89]
	v_mfma_f32_16x16x32_bf16 v[82:85], v[182:185], v[216:219], v[82:85]
	v_mfma_f32_16x16x32_bf16 v[70:73], v[172:175], v[224:227], v[70:73]
	v_mfma_f32_16x16x32_bf16 v[66:69], v[182:185], v[224:227], v[66:69]
	s_setprio 0
	s_barrier
	s_add_i32 s56, s28, s25
	s_mov_b32 m0, s56
	ds_read_b128 v[186:189], v145 offset:16384
	ds_read_b128 v[190:193], v145 offset:17408
	ds_read_b128 v[194:197], v145 offset:18432
	ds_read_b128 v[204:207], v145 offset:19456
	ds_read_b128 v[208:211], v145 offset:20480
	ds_read_b128 v[216:219], v145 offset:21504
	ds_read_b128 v[220:223], v145 offset:22528
	ds_read_b128 v[224:227], v145 offset:23552
	global_load_lds_dwordx4 v134, s[20:21]
	s_add_i32 m0, s56, 0x2000
	s_add_u32 s58, s20, 0x80000
	s_addc_u32 s59, s21, 0
	s_add_i32 s34, s34, s25
	global_load_lds_dwordx4 v130, s[20:21]
	s_mov_b32 m0, s34
	s_nop 0
	global_load_lds_dwordx4 v134, s[58:59]
	s_add_i32 m0, s34, 0x2000
	s_nop 0
	global_load_lds_dwordx4 v130, s[58:59]
	s_mov_b32 m0, s26
	s_nop 0
	global_load_lds_dwordx4 v136, s[22:23]
	s_mov_b32 m0, s27
	s_nop 0
	global_load_lds_dwordx4 v132, s[22:23]
	s_waitcnt vmcnt(8)
	s_waitcnt lgkmcnt(0)
	s_barrier
	s_setprio 1
	s_waitcnt lgkmcnt(0)
	v_mfma_f32_16x16x32_bf16 v[62:65], v[146:149], v[186:189], v[62:65]
	v_mfma_f32_16x16x32_bf16 v[58:61], v[154:157], v[186:189], v[58:61]
	v_mfma_f32_16x16x32_bf16 v[46:49], v[146:149], v[194:197], v[46:49]
	v_mfma_f32_16x16x32_bf16 v[42:45], v[154:157], v[194:197], v[42:45]
	v_mfma_f32_16x16x32_bf16 v[30:33], v[146:149], v[208:211], v[30:33]
	v_mfma_f32_16x16x32_bf16 v[26:29], v[154:157], v[208:211], v[26:29]
	v_mfma_f32_16x16x32_bf16 v[14:17], v[146:149], v[220:223], v[14:17]
	v_mfma_f32_16x16x32_bf16 v[10:13], v[154:157], v[220:223], v[10:13]
	v_mfma_f32_16x16x32_bf16 v[62:65], v[150:153], v[190:193], v[62:65]
	v_mfma_f32_16x16x32_bf16 v[58:61], v[158:161], v[190:193], v[58:61]
	v_mfma_f32_16x16x32_bf16 v[46:49], v[150:153], v[204:207], v[46:49]
	v_mfma_f32_16x16x32_bf16 v[42:45], v[158:161], v[204:207], v[42:45]
	v_mfma_f32_16x16x32_bf16 v[30:33], v[150:153], v[216:219], v[30:33]
	v_mfma_f32_16x16x32_bf16 v[26:29], v[158:161], v[216:219], v[26:29]
	v_mfma_f32_16x16x32_bf16 v[14:17], v[150:153], v[224:227], v[14:17]
	v_mfma_f32_16x16x32_bf16 v[10:13], v[158:161], v[224:227], v[10:13]
	s_setprio 0
	s_setprio 1
	v_mfma_f32_16x16x32_bf16 v[54:57], v[168:171], v[186:189], v[54:57]
	v_mfma_f32_16x16x32_bf16 v[50:53], v[176:179], v[186:189], v[50:53]
	v_mfma_f32_16x16x32_bf16 v[38:41], v[168:171], v[194:197], v[38:41]
	v_mfma_f32_16x16x32_bf16 v[34:37], v[176:179], v[194:197], v[34:37]
	v_mfma_f32_16x16x32_bf16 v[22:25], v[168:171], v[208:211], v[22:25]
	v_mfma_f32_16x16x32_bf16 v[18:21], v[176:179], v[208:211], v[18:21]
	v_mfma_f32_16x16x32_bf16 v[6:9], v[168:171], v[220:223], v[6:9]
	v_mfma_f32_16x16x32_bf16 v[2:5], v[176:179], v[220:223], v[2:5]
	v_mfma_f32_16x16x32_bf16 v[54:57], v[172:175], v[190:193], v[54:57]
	v_mfma_f32_16x16x32_bf16 v[50:53], v[182:185], v[190:193], v[50:53]
	v_mfma_f32_16x16x32_bf16 v[38:41], v[172:175], v[204:207], v[38:41]
	v_mfma_f32_16x16x32_bf16 v[34:37], v[182:185], v[204:207], v[34:37]
	v_mfma_f32_16x16x32_bf16 v[22:25], v[172:175], v[216:219], v[22:25]
	v_mfma_f32_16x16x32_bf16 v[18:21], v[182:185], v[216:219], v[18:21]
	v_mfma_f32_16x16x32_bf16 v[6:9], v[172:175], v[224:227], v[6:9]
	v_mfma_f32_16x16x32_bf16 v[2:5], v[182:185], v[224:227], v[2:5]
	s_setprio 0
	s_barrier
	v_add_u32_e32 v0, s29, v144
	s_add_i32 s34, 0, 0x1c000
	ds_read_b128 v[146:149], v0
	ds_read_b128 v[150:153], v0 offset:1024
	ds_read_b128 v[154:157], v0 offset:2048
	ds_read_b128 v[158:161], v0 offset:3072
	v_add_u32_e32 v0, s34, v144
	ds_read_b128 v[168:171], v0
	ds_read_b128 v[172:175], v0 offset:1024
	ds_read_b128 v[176:179], v0 offset:2048
	ds_read_b128 v[182:185], v0 offset:3072
	s_add_u32 s22, s22, 0x80000
	s_addc_u32 s23, s23, 0
	s_mov_b32 m0, s31
	ds_read_b128 v[186:189], v145 offset:32768
	ds_read_b128 v[190:193], v145 offset:33792
	ds_read_b128 v[194:197], v145 offset:34816
	ds_read_b128 v[204:207], v145 offset:35840
	ds_read_b128 v[208:211], v145 offset:36864
	ds_read_b128 v[216:219], v145 offset:37888
	ds_read_b128 v[220:223], v145 offset:38912
	ds_read_b128 v[224:227], v145 offset:39936
	global_load_lds_dwordx4 v136, s[22:23]
	s_mov_b32 m0, s35
	s_nop 0
	global_load_lds_dwordx4 v132, s[22:23]
	s_waitcnt vmcnt(8)
	s_waitcnt lgkmcnt(0)
	s_barrier
	s_setprio 1
	s_waitcnt lgkmcnt(0)
	v_mfma_f32_16x16x32_bf16 v[126:129], v[146:149], v[186:189], v[126:129]
	v_mfma_f32_16x16x32_bf16 v[122:125], v[154:157], v[186:189], v[122:125]
	v_mfma_f32_16x16x32_bf16 v[110:113], v[146:149], v[194:197], v[110:113]
	v_mfma_f32_16x16x32_bf16 v[106:109], v[154:157], v[194:197], v[106:109]
	v_mfma_f32_16x16x32_bf16 v[94:97], v[146:149], v[208:211], v[94:97]
	v_mfma_f32_16x16x32_bf16 v[90:93], v[154:157], v[208:211], v[90:93]
	v_mfma_f32_16x16x32_bf16 v[78:81], v[146:149], v[220:223], v[78:81]
	v_mfma_f32_16x16x32_bf16 v[74:77], v[154:157], v[220:223], v[74:77]
	v_mfma_f32_16x16x32_bf16 v[126:129], v[150:153], v[190:193], v[126:129]
	v_mfma_f32_16x16x32_bf16 v[122:125], v[158:161], v[190:193], v[122:125]
	v_mfma_f32_16x16x32_bf16 v[110:113], v[150:153], v[204:207], v[110:113]
	v_mfma_f32_16x16x32_bf16 v[106:109], v[158:161], v[204:207], v[106:109]
	v_mfma_f32_16x16x32_bf16 v[94:97], v[150:153], v[216:219], v[94:97]
	v_mfma_f32_16x16x32_bf16 v[90:93], v[158:161], v[216:219], v[90:93]
	v_mfma_f32_16x16x32_bf16 v[78:81], v[150:153], v[224:227], v[78:81]
	v_mfma_f32_16x16x32_bf16 v[74:77], v[158:161], v[224:227], v[74:77]
	s_setprio 0
	s_setprio 1
	v_mfma_f32_16x16x32_bf16 v[118:121], v[168:171], v[186:189], v[118:121]
	v_mfma_f32_16x16x32_bf16 v[114:117], v[176:179], v[186:189], v[114:117]
	v_mfma_f32_16x16x32_bf16 v[102:105], v[168:171], v[194:197], v[102:105]
	v_mfma_f32_16x16x32_bf16 v[98:101], v[176:179], v[194:197], v[98:101]
	v_mfma_f32_16x16x32_bf16 v[86:89], v[168:171], v[208:211], v[86:89]
	v_mfma_f32_16x16x32_bf16 v[82:85], v[176:179], v[208:211], v[82:85]
	v_mfma_f32_16x16x32_bf16 v[70:73], v[168:171], v[220:223], v[70:73]
	v_mfma_f32_16x16x32_bf16 v[66:69], v[176:179], v[220:223], v[66:69]
	v_mfma_f32_16x16x32_bf16 v[118:121], v[172:175], v[190:193], v[118:121]
	v_mfma_f32_16x16x32_bf16 v[114:117], v[182:185], v[190:193], v[114:117]
	v_mfma_f32_16x16x32_bf16 v[102:105], v[172:175], v[204:207], v[102:105]
	v_mfma_f32_16x16x32_bf16 v[98:101], v[182:185], v[204:207], v[98:101]
	v_mfma_f32_16x16x32_bf16 v[86:89], v[172:175], v[216:219], v[86:89]
	v_mfma_f32_16x16x32_bf16 v[82:85], v[182:185], v[216:219], v[82:85]
	v_mfma_f32_16x16x32_bf16 v[70:73], v[172:175], v[224:227], v[70:73]
	v_mfma_f32_16x16x32_bf16 v[66:69], v[182:185], v[224:227], v[66:69]
	s_setprio 0
	s_barrier
	s_add_u32 s100, s22, 0xfff80080
	s_addc_u32 s101, s23, -1
	s_add_u32 s98, s20, 0x80
	s_addc_u32 s99, s21, 0
	s_add_i32 s22, s29, s25
	s_mov_b32 m0, s22
	ds_read_b128 v[186:189], v145 offset:49152
	ds_read_b128 v[190:193], v145 offset:50176
	ds_read_b128 v[194:197], v145 offset:51200
	ds_read_b128 v[204:207], v145 offset:52224
	ds_read_b128 v[208:211], v145 offset:53248
	ds_read_b128 v[216:219], v145 offset:54272
	ds_read_b128 v[220:223], v145 offset:55296
	ds_read_b128 v[224:227], v145 offset:56320
	global_load_lds_dwordx4 v134, s[98:99]
	s_add_i32 m0, s22, 0x2000
	s_add_u32 s20, s20, 0x80080
	s_addc_u32 s21, s21, 0
	s_add_i32 s22, s34, s25
	global_load_lds_dwordx4 v130, s[98:99]
	s_mov_b32 m0, s22
	s_nop 0
	global_load_lds_dwordx4 v134, s[20:21]
	s_add_i32 m0, s22, 0x2000
	s_nop 0
	global_load_lds_dwordx4 v130, s[20:21]
	s_mov_b32 m0, s38
	s_nop 0
	global_load_lds_dwordx4 v136, s[100:101]
	s_mov_b32 m0, s39
	s_nop 0
	global_load_lds_dwordx4 v132, s[100:101]
	s_waitcnt vmcnt(8)
	s_waitcnt lgkmcnt(0)
	s_barrier
	s_setprio 1
	s_waitcnt lgkmcnt(0)
	v_mfma_f32_16x16x32_bf16 v[62:65], v[146:149], v[186:189], v[62:65]
	v_mfma_f32_16x16x32_bf16 v[58:61], v[154:157], v[186:189], v[58:61]
	v_mfma_f32_16x16x32_bf16 v[46:49], v[146:149], v[194:197], v[46:49]
	v_mfma_f32_16x16x32_bf16 v[42:45], v[154:157], v[194:197], v[42:45]
	v_mfma_f32_16x16x32_bf16 v[30:33], v[146:149], v[208:211], v[30:33]
	v_mfma_f32_16x16x32_bf16 v[26:29], v[154:157], v[208:211], v[26:29]
	v_mfma_f32_16x16x32_bf16 v[14:17], v[146:149], v[220:223], v[14:17]
	v_mfma_f32_16x16x32_bf16 v[10:13], v[154:157], v[220:223], v[10:13]
	v_mfma_f32_16x16x32_bf16 v[62:65], v[150:153], v[190:193], v[62:65]
	v_mfma_f32_16x16x32_bf16 v[58:61], v[158:161], v[190:193], v[58:61]
	v_mfma_f32_16x16x32_bf16 v[46:49], v[150:153], v[204:207], v[46:49]
	v_mfma_f32_16x16x32_bf16 v[42:45], v[158:161], v[204:207], v[42:45]
	v_mfma_f32_16x16x32_bf16 v[30:33], v[150:153], v[216:219], v[30:33]
	v_mfma_f32_16x16x32_bf16 v[26:29], v[158:161], v[216:219], v[26:29]
	v_mfma_f32_16x16x32_bf16 v[14:17], v[150:153], v[224:227], v[14:17]
	v_mfma_f32_16x16x32_bf16 v[10:13], v[158:161], v[224:227], v[10:13]
	s_setprio 0
	s_setprio 1
	v_mfma_f32_16x16x32_bf16 v[54:57], v[168:171], v[186:189], v[54:57]
	v_mfma_f32_16x16x32_bf16 v[50:53], v[176:179], v[186:189], v[50:53]
	v_mfma_f32_16x16x32_bf16 v[38:41], v[168:171], v[194:197], v[38:41]
	v_mfma_f32_16x16x32_bf16 v[34:37], v[176:179], v[194:197], v[34:37]
	v_mfma_f32_16x16x32_bf16 v[22:25], v[168:171], v[208:211], v[22:25]
	v_mfma_f32_16x16x32_bf16 v[18:21], v[176:179], v[208:211], v[18:21]
	v_mfma_f32_16x16x32_bf16 v[6:9], v[168:171], v[220:223], v[6:9]
	v_mfma_f32_16x16x32_bf16 v[2:5], v[176:179], v[220:223], v[2:5]
	v_mfma_f32_16x16x32_bf16 v[54:57], v[172:175], v[190:193], v[54:57]
	v_mfma_f32_16x16x32_bf16 v[50:53], v[182:185], v[190:193], v[50:53]
	v_mfma_f32_16x16x32_bf16 v[38:41], v[172:175], v[204:207], v[38:41]
	v_mfma_f32_16x16x32_bf16 v[34:37], v[182:185], v[204:207], v[34:37]
	v_mfma_f32_16x16x32_bf16 v[22:25], v[172:175], v[216:219], v[22:25]
	v_mfma_f32_16x16x32_bf16 v[18:21], v[182:185], v[216:219], v[18:21]
	v_mfma_f32_16x16x32_bf16 v[6:9], v[172:175], v[224:227], v[6:9]
	v_mfma_f32_16x16x32_bf16 v[2:5], v[182:185], v[224:227], v[2:5]
	s_setprio 0
	s_barrier
	s_add_i32 s51, s51, 2
	s_add_u32 s18, s18, 0x100
	s_addc_u32 s19, s19, 0
	s_add_u32 s13, s13, 0x100
	s_addc_u32 s50, s50, 0
	s_cmp_gt_u32 s51, 29
	s_cbranch_scc0 .LBB0_1151
	s_and_b64 vcc, exec, s[8:9]
	s_cbranch_vccz .LBB0_1154
	s_barrier
